# BM selected-attention: check lane-local max against rescale threshold first; permlane column-max reduction only on the rare rescale path
# speedup vs baseline: 1.0088x; 1.0042x over previous
.Lbm2_Ag0_max:
	v_max3_f32 v198, v84, v85, v86
	v_max3_f32 v199, v87, v88, v89
	v_max3_f32 v198, v198, v90, v91
	v_max3_f32 v199, v199, v92, v93
	v_max3_f32 v198, v198, v94, v95
	v_max3_f32 v199, v199, v96, v97
	v_max3_f32 v198, v198, v98, v99
	v_max_f32_e32 v198, v198, v199
	v_cmp_gt_f32_e32 vcc, v198, v78
	s_cbranch_vccnz .Lbm2_Ag0_resc

.Lbm2_Ag0_resc:
	v_mov_b32_e32 v199, v198
	s_nop 1
	v_permlane16_swap_b32_e32 v198, v199
	s_nop 0
	v_max_f32_e32 v198, v198, v199
	v_mov_b32_e32 v199, v198
	s_nop 1
	v_permlane32_swap_b32_e32 v198, v199
	s_nop 0
	v_max_f32_e32 v198, v198, v199
	v_max_f32_e32 v248, 0, v198
	v_max_f32_e32 v249, v198, v78
	v_exp_f32_e64 v248, -v248
	v_sub_f32_e32 v190, v190, v249
	v_sub_f32_e32 v84, v84, v249
	v_sub_f32_e32 v85, v85, v249
	v_sub_f32_e32 v86, v86, v249
	v_sub_f32_e32 v87, v87, v249
	v_sub_f32_e32 v88, v88, v249
	v_sub_f32_e32 v89, v89, v249
	v_sub_f32_e32 v90, v90, v249
	v_sub_f32_e32 v91, v91, v249
	v_sub_f32_e32 v92, v92, v249
	v_sub_f32_e32 v93, v93, v249
	v_sub_f32_e32 v94, v94, v249
	v_sub_f32_e32 v95, v95, v249
	v_sub_f32_e32 v96, v96, v249
	v_sub_f32_e32 v97, v97, v249
	v_sub_f32_e32 v98, v98, v249
	v_sub_f32_e32 v99, v99, v249
	v_mul_f32_e32 v194, v194, v248
	v_pk_mul_f32 v[100:101], v[100:101], v[248:249] op_sel_hi:[1,0]
	v_pk_mul_f32 v[102:103], v[102:103], v[248:249] op_sel_hi:[1,0]
	v_pk_mul_f32 v[104:105], v[104:105], v[248:249] op_sel_hi:[1,0]
	v_pk_mul_f32 v[106:107], v[106:107], v[248:249] op_sel_hi:[1,0]
	v_pk_mul_f32 v[108:109], v[108:109], v[248:249] op_sel_hi:[1,0]
	v_pk_mul_f32 v[110:111], v[110:111], v[248:249] op_sel_hi:[1,0]
	v_pk_mul_f32 v[112:113], v[112:113], v[248:249] op_sel_hi:[1,0]
	v_pk_mul_f32 v[114:115], v[114:115], v[248:249] op_sel_hi:[1,0]
	s_branch .Lbm2_Ag0_exp

.Lbm2_Ag1_resc:
	v_mov_b32_e32 v199, v198
	s_nop 1
	v_permlane16_swap_b32_e32 v198, v199
	s_nop 0
	v_max_f32_e32 v198, v198, v199
	v_mov_b32_e32 v199, v198
	s_nop 1
	v_permlane32_swap_b32_e32 v198, v199
	s_nop 0
	v_max_f32_e32 v198, v198, v199
	v_max_f32_e32 v248, 0, v198
	v_max_f32_e32 v249, v198, v78
	v_exp_f32_e64 v248, -v248
	v_sub_f32_e32 v191, v191, v249
	v_sub_f32_e32 v84, v84, v249
	v_sub_f32_e32 v85, v85, v249
	v_sub_f32_e32 v86, v86, v249
	v_sub_f32_e32 v87, v87, v249
	v_sub_f32_e32 v88, v88, v249
	v_sub_f32_e32 v89, v89, v249
	v_sub_f32_e32 v90, v90, v249
	v_sub_f32_e32 v91, v91, v249
	v_sub_f32_e32 v92, v92, v249
	v_sub_f32_e32 v93, v93, v249
	v_sub_f32_e32 v94, v94, v249
	v_sub_f32_e32 v95, v95, v249
	v_sub_f32_e32 v96, v96, v249
	v_sub_f32_e32 v97, v97, v249
	v_sub_f32_e32 v98, v98, v249
	v_sub_f32_e32 v99, v99, v249
	v_mul_f32_e32 v195, v195, v248
	v_pk_mul_f32 v[116:117], v[116:117], v[248:249] op_sel_hi:[1,0]
	v_pk_mul_f32 v[118:119], v[118:119], v[248:249] op_sel_hi:[1,0]
	v_pk_mul_f32 v[120:121], v[120:121], v[248:249] op_sel_hi:[1,0]
	v_pk_mul_f32 v[122:123], v[122:123], v[248:249] op_sel_hi:[1,0]
	v_pk_mul_f32 v[124:125], v[124:125], v[248:249] op_sel_hi:[1,0]
	v_pk_mul_f32 v[126:127], v[126:127], v[248:249] op_sel_hi:[1,0]
	v_pk_mul_f32 v[128:129], v[128:129], v[248:249] op_sel_hi:[1,0]
	v_pk_mul_f32 v[130:131], v[130:131], v[248:249] op_sel_hi:[1,0]
	s_branch .Lbm2_Ag1_exp

.Lbm2_Ag2_resc:
	v_mov_b32_e32 v199, v198
	s_nop 1
	v_permlane16_swap_b32_e32 v198, v199
	s_nop 0
	v_max_f32_e32 v198, v198, v199
	v_mov_b32_e32 v199, v198
	s_nop 1
	v_permlane32_swap_b32_e32 v198, v199
	s_nop 0
	v_max_f32_e32 v198, v198, v199
	v_max_f32_e32 v248, 0, v198
	v_max_f32_e32 v249, v198, v78
	v_exp_f32_e64 v248, -v248
	v_sub_f32_e32 v192, v192, v249
	v_sub_f32_e32 v84, v84, v249
	v_sub_f32_e32 v85, v85, v249
	v_sub_f32_e32 v86, v86, v249
	v_sub_f32_e32 v87, v87, v249
	v_sub_f32_e32 v88, v88, v249
	v_sub_f32_e32 v89, v89, v249
	v_sub_f32_e32 v90, v90, v249
	v_sub_f32_e32 v91, v91, v249
	v_sub_f32_e32 v92, v92, v249
	v_sub_f32_e32 v93, v93, v249
	v_sub_f32_e32 v94, v94, v249
	v_sub_f32_e32 v95, v95, v249
	v_sub_f32_e32 v96, v96, v249
	v_sub_f32_e32 v97, v97, v249
	v_sub_f32_e32 v98, v98, v249
	v_sub_f32_e32 v99, v99, v249
	v_mul_f32_e32 v196, v196, v248
	v_pk_mul_f32 v[132:133], v[132:133], v[248:249] op_sel_hi:[1,0]
	v_pk_mul_f32 v[134:135], v[134:135], v[248:249] op_sel_hi:[1,0]
	v_pk_mul_f32 v[136:137], v[136:137], v[248:249] op_sel_hi:[1,0]
	v_pk_mul_f32 v[138:139], v[138:139], v[248:249] op_sel_hi:[1,0]
	v_pk_mul_f32 v[140:141], v[140:141], v[248:249] op_sel_hi:[1,0]
	v_pk_mul_f32 v[142:143], v[142:143], v[248:249] op_sel_hi:[1,0]
	v_pk_mul_f32 v[144:145], v[144:145], v[248:249] op_sel_hi:[1,0]
	v_pk_mul_f32 v[146:147], v[146:147], v[248:249] op_sel_hi:[1,0]
	s_branch .Lbm2_Ag2_exp

.Lbm2_Ag3_resc:
	v_mov_b32_e32 v199, v198
	s_nop 1
	v_permlane16_swap_b32_e32 v198, v199
	s_nop 0
	v_max_f32_e32 v198, v198, v199
	v_mov_b32_e32 v199, v198
	s_nop 1
	v_permlane32_swap_b32_e32 v198, v199
	s_nop 0
	v_max_f32_e32 v198, v198, v199
	v_max_f32_e32 v248, 0, v198
	v_max_f32_e32 v249, v198, v78
	v_exp_f32_e64 v248, -v248
	v_sub_f32_e32 v193, v193, v249
	v_sub_f32_e32 v84, v84, v249
	v_sub_f32_e32 v85, v85, v249
	v_sub_f32_e32 v86, v86, v249
	v_sub_f32_e32 v87, v87, v249
	v_sub_f32_e32 v88, v88, v249
	v_sub_f32_e32 v89, v89, v249
	v_sub_f32_e32 v90, v90, v249
	v_sub_f32_e32 v91, v91, v249
	v_sub_f32_e32 v92, v92, v249
	v_sub_f32_e32 v93, v93, v249
	v_sub_f32_e32 v94, v94, v249
	v_sub_f32_e32 v95, v95, v249
	v_sub_f32_e32 v96, v96, v249
	v_sub_f32_e32 v97, v97, v249
	v_sub_f32_e32 v98, v98, v249
	v_sub_f32_e32 v99, v99, v249
	v_mul_f32_e32 v197, v197, v248
	v_pk_mul_f32 v[148:149], v[148:149], v[248:249] op_sel_hi:[1,0]
	v_pk_mul_f32 v[150:151], v[150:151], v[248:249] op_sel_hi:[1,0]
	v_pk_mul_f32 v[152:153], v[152:153], v[248:249] op_sel_hi:[1,0]
	v_pk_mul_f32 v[154:155], v[154:155], v[248:249] op_sel_hi:[1,0]
	v_pk_mul_f32 v[156:157], v[156:157], v[248:249] op_sel_hi:[1,0]
	v_pk_mul_f32 v[158:159], v[158:159], v[248:249] op_sel_hi:[1,0]
	v_pk_mul_f32 v[160:161], v[160:161], v[248:249] op_sel_hi:[1,0]
	v_pk_mul_f32 v[162:163], v[162:163], v[248:249] op_sel_hi:[1,0]
	s_branch .Lbm2_Ag3_exp
